# LN hand-written + scan consumer hand-written (packed f32, LDS reads prefetched 2 steps ahead)
# speedup vs baseline: 1.0886x; 1.0055x over previous
.LBB0_1235:
	s_and_b64 s[42:43], s[42:43], exec
	s_cselect_b32 s42, 0, s66
	v_add_u32_e32 v8, s42, v32
	s_cselect_b32 s42, s68, s67
	v_lshl_add_u32 v4, v75, 2, s42
	v_lshl_add_u64 v[28:29], v[26:27], 0, s[40:41]
	ds_read2st64_b32 v[212:213], v4 offset0:0 offset1:1
	ds_read_b128 v[88:91], v8 offset:32768
	ds_read_b128 v[80:83], v8 offset:8192
	ds_read_b128 v[84:87], v8 offset:24576
	ds_read_b128 v[92:95], v8 offset:40960
	ds_read_b128 v[76:79], v8 offset:0
	ds_read_b128 v[108:111], v8 offset:33024
	ds_read_b128 v[100:103], v8 offset:8448
	ds_read_b128 v[104:107], v8 offset:24832
	ds_read_b128 v[112:115], v8 offset:41216
	ds_read_b128 v[96:99], v8 offset:256
	v_readfirstlane_b32 s44, v28
	v_readfirstlane_b32 s45, v29
	s_nop 3
	v_subrev_u32_e32 v5, s44, v28
	s_add_u32 s44, s44, 0x23501000
	s_addc_u32 s45, s45, 0
	s_waitcnt lgkmcnt(5)
	ds_read2st64_b32 v[214:215], v4 offset0:2 offset1:3
	ds_read_b128 v[184:187], v8 offset:33280
	ds_read_b128 v[176:179], v8 offset:8704
	ds_read_b128 v[180:183], v8 offset:25088
	ds_read_b128 v[188:191], v8 offset:41472
	ds_read_b128 v[172:175], v8 offset:512
	v_pk_mul_f32 v[216:217], v[0:1], v[88:89]
	v_pk_fma_f32 v[216:217], v[2:3], v[90:91], v[216:217]
	v_add_f32_e32 v216, v216, v217
	s_nop 0
	v_pk_mul_f32 v[220:221], v[80:81], v[212:213] op_sel_hi:[1,0]
	v_add_f32_dpp v216, v216, v216 quad_perm:[1,0,3,2] row_mask:0xf bank_mask:0xf bound_ctrl:1
	s_nop 0
	v_pk_mul_f32 v[222:223], v[82:83], v[212:213] op_sel_hi:[1,0]
	v_add_f32_dpp v216, v216, v216 quad_perm:[2,3,0,1] row_mask:0xf bank_mask:0xf bound_ctrl:1
	s_nop 0
	v_pk_fma_f32 v[220:221], v[0:1], v[84:85], v[220:221]
	v_add_f32_dpp v216, v216, v216 row_half_mirror row_mask:0xf bank_mask:0xf bound_ctrl:1
	s_nop 0
	v_pk_fma_f32 v[222:223], v[2:3], v[86:87], v[222:223]
	v_add_f32_dpp v216, v216, v216 row_mirror row_mask:0xf bank_mask:0xf bound_ctrl:1
	v_pk_fma_f32 v[0:1], v[92:93], v[216:217], v[220:221] op_sel_hi:[1,0,1] neg_lo:[1,0,0] neg_hi:[1,0,0]
	v_pk_fma_f32 v[2:3], v[94:95], v[216:217], v[222:223] op_sel_hi:[1,0,1] neg_lo:[1,0,0] neg_hi:[1,0,0]
	s_waitcnt lgkmcnt(6)
	ds_read_b128 v[204:207], v8 offset:33536
	ds_read_b128 v[196:199], v8 offset:8960
	ds_read_b128 v[200:203], v8 offset:25344
	ds_read_b128 v[208:211], v8 offset:41728
	ds_read_b128 v[192:195], v8 offset:768
	v_pk_mul_f32 v[216:217], v[0:1], v[108:109]
	v_pk_mul_f32 v[218:219], v[0:1], v[76:77]
	v_pk_fma_f32 v[216:217], v[2:3], v[110:111], v[216:217]
	v_pk_fma_f32 v[218:219], v[2:3], v[78:79], v[218:219]
	v_add_f32_e32 v216, v216, v217
	v_add_f32_e32 v218, v218, v219
	v_pk_mul_f32 v[220:221], v[100:101], v[212:213] op_sel:[0,1]
	v_add_f32_dpp v216, v216, v216 quad_perm:[1,0,3,2] row_mask:0xf bank_mask:0xf bound_ctrl:1
	v_add_f32_dpp v218, v218, v218 quad_perm:[1,0,3,2] row_mask:0xf bank_mask:0xf bound_ctrl:1
	v_pk_mul_f32 v[222:223], v[102:103], v[212:213] op_sel:[0,1]
	v_add_f32_dpp v216, v216, v216 quad_perm:[2,3,0,1] row_mask:0xf bank_mask:0xf bound_ctrl:1
	v_add_f32_dpp v218, v218, v218 quad_perm:[2,3,0,1] row_mask:0xf bank_mask:0xf bound_ctrl:1
	v_pk_fma_f32 v[220:221], v[0:1], v[104:105], v[220:221]
	v_add_f32_dpp v216, v216, v216 row_half_mirror row_mask:0xf bank_mask:0xf bound_ctrl:1
	v_add_f32_dpp v218, v218, v218 row_half_mirror row_mask:0xf bank_mask:0xf bound_ctrl:1
	v_pk_fma_f32 v[222:223], v[2:3], v[106:107], v[222:223]
	v_add_f32_dpp v216, v216, v216 row_mirror row_mask:0xf bank_mask:0xf bound_ctrl:1
	v_add_f32_dpp v226, v218, v218 row_mirror row_mask:0xf bank_mask:0xf bound_ctrl:1
	v_pk_fma_f32 v[0:1], v[112:113], v[216:217], v[220:221] op_sel_hi:[1,0,1] neg_lo:[1,0,0] neg_hi:[1,0,0]
	v_pk_fma_f32 v[2:3], v[114:115], v[216:217], v[222:223] op_sel_hi:[1,0,1] neg_lo:[1,0,0] neg_hi:[1,0,0]
	global_store_dword v5, v226, s[44:45] offset:-4096
	s_waitcnt lgkmcnt(5)
	ds_read2st64_b32 v[212:213], v4 offset0:4 offset1:5
	ds_read_b128 v[88:91], v8 offset:33792
	ds_read_b128 v[80:83], v8 offset:9216
	ds_read_b128 v[84:87], v8 offset:25600
	ds_read_b128 v[92:95], v8 offset:41984
	ds_read_b128 v[76:79], v8 offset:1024
	v_pk_mul_f32 v[216:217], v[0:1], v[184:185]
	v_pk_mul_f32 v[218:219], v[0:1], v[96:97]
	v_pk_fma_f32 v[216:217], v[2:3], v[186:187], v[216:217]
	v_pk_fma_f32 v[218:219], v[2:3], v[98:99], v[218:219]
	v_add_f32_e32 v216, v216, v217
	v_add_f32_e32 v218, v218, v219
	v_pk_mul_f32 v[220:221], v[176:177], v[214:215] op_sel_hi:[1,0]
	v_add_f32_dpp v216, v216, v216 quad_perm:[1,0,3,2] row_mask:0xf bank_mask:0xf bound_ctrl:1
	v_add_f32_dpp v218, v218, v218 quad_perm:[1,0,3,2] row_mask:0xf bank_mask:0xf bound_ctrl:1
	v_pk_mul_f32 v[222:223], v[178:179], v[214:215] op_sel_hi:[1,0]
	v_add_f32_dpp v216, v216, v216 quad_perm:[2,3,0,1] row_mask:0xf bank_mask:0xf bound_ctrl:1
	v_add_f32_dpp v218, v218, v218 quad_perm:[2,3,0,1] row_mask:0xf bank_mask:0xf bound_ctrl:1
	v_pk_fma_f32 v[220:221], v[0:1], v[180:181], v[220:221]
	v_add_f32_dpp v216, v216, v216 row_half_mirror row_mask:0xf bank_mask:0xf bound_ctrl:1
	v_add_f32_dpp v218, v218, v218 row_half_mirror row_mask:0xf bank_mask:0xf bound_ctrl:1
	v_pk_fma_f32 v[222:223], v[2:3], v[182:183], v[222:223]
	v_add_f32_dpp v216, v216, v216 row_mirror row_mask:0xf bank_mask:0xf bound_ctrl:1
	v_add_f32_dpp v227, v218, v218 row_mirror row_mask:0xf bank_mask:0xf bound_ctrl:1
	v_pk_fma_f32 v[0:1], v[188:189], v[216:217], v[220:221] op_sel_hi:[1,0,1] neg_lo:[1,0,0] neg_hi:[1,0,0]
	v_pk_fma_f32 v[2:3], v[190:191], v[216:217], v[222:223] op_sel_hi:[1,0,1] neg_lo:[1,0,0] neg_hi:[1,0,0]
	global_store_dword v5, v227, s[44:45] offset:0
	s_add_u32 s44, s44, 0x2000
	s_addc_u32 s45, s45, 0
	s_waitcnt lgkmcnt(6)
	ds_read_b128 v[108:111], v8 offset:34048
	ds_read_b128 v[100:103], v8 offset:9472
	ds_read_b128 v[104:107], v8 offset:25856
	ds_read_b128 v[112:115], v8 offset:42240
	ds_read_b128 v[96:99], v8 offset:1280
	v_pk_mul_f32 v[216:217], v[0:1], v[204:205]
	v_pk_mul_f32 v[218:219], v[0:1], v[172:173]
	v_pk_fma_f32 v[216:217], v[2:3], v[206:207], v[216:217]
	v_pk_fma_f32 v[218:219], v[2:3], v[174:175], v[218:219]
	v_add_f32_e32 v216, v216, v217
	v_add_f32_e32 v218, v218, v219
	v_pk_mul_f32 v[220:221], v[196:197], v[214:215] op_sel:[0,1]
	v_add_f32_dpp v216, v216, v216 quad_perm:[1,0,3,2] row_mask:0xf bank_mask:0xf bound_ctrl:1
	v_add_f32_dpp v218, v218, v218 quad_perm:[1,0,3,2] row_mask:0xf bank_mask:0xf bound_ctrl:1
	v_pk_mul_f32 v[222:223], v[198:199], v[214:215] op_sel:[0,1]
	v_add_f32_dpp v216, v216, v216 quad_perm:[2,3,0,1] row_mask:0xf bank_mask:0xf bound_ctrl:1
	v_add_f32_dpp v218, v218, v218 quad_perm:[2,3,0,1] row_mask:0xf bank_mask:0xf bound_ctrl:1
	v_pk_fma_f32 v[220:221], v[0:1], v[200:201], v[220:221]
	v_add_f32_dpp v216, v216, v216 row_half_mirror row_mask:0xf bank_mask:0xf bound_ctrl:1
	v_add_f32_dpp v218, v218, v218 row_half_mirror row_mask:0xf bank_mask:0xf bound_ctrl:1
	v_pk_fma_f32 v[222:223], v[2:3], v[202:203], v[222:223]
	v_add_f32_dpp v216, v216, v216 row_mirror row_mask:0xf bank_mask:0xf bound_ctrl:1
	v_add_f32_dpp v226, v218, v218 row_mirror row_mask:0xf bank_mask:0xf bound_ctrl:1
	v_pk_fma_f32 v[0:1], v[208:209], v[216:217], v[220:221] op_sel_hi:[1,0,1] neg_lo:[1,0,0] neg_hi:[1,0,0]
	v_pk_fma_f32 v[2:3], v[210:211], v[216:217], v[222:223] op_sel_hi:[1,0,1] neg_lo:[1,0,0] neg_hi:[1,0,0]
	global_store_dword v5, v226, s[44:45] offset:-4096
	s_waitcnt lgkmcnt(5)
	ds_read2st64_b32 v[214:215], v4 offset0:6 offset1:7
	ds_read_b128 v[184:187], v8 offset:34304
	ds_read_b128 v[176:179], v8 offset:9728
	ds_read_b128 v[180:183], v8 offset:26112
	ds_read_b128 v[188:191], v8 offset:42496
	ds_read_b128 v[172:175], v8 offset:1536
	v_pk_mul_f32 v[216:217], v[0:1], v[88:89]
	v_pk_mul_f32 v[218:219], v[0:1], v[192:193]
	v_pk_fma_f32 v[216:217], v[2:3], v[90:91], v[216:217]
	v_pk_fma_f32 v[218:219], v[2:3], v[194:195], v[218:219]
	v_add_f32_e32 v216, v216, v217
	v_add_f32_e32 v218, v218, v219
	v_pk_mul_f32 v[220:221], v[80:81], v[212:213] op_sel_hi:[1,0]
	v_add_f32_dpp v216, v216, v216 quad_perm:[1,0,3,2] row_mask:0xf bank_mask:0xf bound_ctrl:1
	v_add_f32_dpp v218, v218, v218 quad_perm:[1,0,3,2] row_mask:0xf bank_mask:0xf bound_ctrl:1
	v_pk_mul_f32 v[222:223], v[82:83], v[212:213] op_sel_hi:[1,0]
	v_add_f32_dpp v216, v216, v216 quad_perm:[2,3,0,1] row_mask:0xf bank_mask:0xf bound_ctrl:1
	v_add_f32_dpp v218, v218, v218 quad_perm:[2,3,0,1] row_mask:0xf bank_mask:0xf bound_ctrl:1
	v_pk_fma_f32 v[220:221], v[0:1], v[84:85], v[220:221]
	v_add_f32_dpp v216, v216, v216 row_half_mirror row_mask:0xf bank_mask:0xf bound_ctrl:1
	v_add_f32_dpp v218, v218, v218 row_half_mirror row_mask:0xf bank_mask:0xf bound_ctrl:1
	v_pk_fma_f32 v[222:223], v[2:3], v[86:87], v[222:223]
	v_add_f32_dpp v216, v216, v216 row_mirror row_mask:0xf bank_mask:0xf bound_ctrl:1
	v_add_f32_dpp v227, v218, v218 row_mirror row_mask:0xf bank_mask:0xf bound_ctrl:1
	v_pk_fma_f32 v[0:1], v[92:93], v[216:217], v[220:221] op_sel_hi:[1,0,1] neg_lo:[1,0,0] neg_hi:[1,0,0]
	v_pk_fma_f32 v[2:3], v[94:95], v[216:217], v[222:223] op_sel_hi:[1,0,1] neg_lo:[1,0,0] neg_hi:[1,0,0]
	global_store_dword v5, v227, s[44:45] offset:0
	s_add_u32 s44, s44, 0x2000
	s_addc_u32 s45, s45, 0
	s_waitcnt lgkmcnt(6)
	ds_read_b128 v[204:207], v8 offset:34560
	ds_read_b128 v[196:199], v8 offset:9984
	ds_read_b128 v[200:203], v8 offset:26368
	ds_read_b128 v[208:211], v8 offset:42752
	ds_read_b128 v[192:195], v8 offset:1792
	v_pk_mul_f32 v[216:217], v[0:1], v[108:109]
	v_pk_mul_f32 v[218:219], v[0:1], v[76:77]
	v_pk_fma_f32 v[216:217], v[2:3], v[110:111], v[216:217]
	v_pk_fma_f32 v[218:219], v[2:3], v[78:79], v[218:219]
	v_add_f32_e32 v216, v216, v217
	v_add_f32_e32 v218, v218, v219
	v_pk_mul_f32 v[220:221], v[100:101], v[212:213] op_sel:[0,1]
	v_add_f32_dpp v216, v216, v216 quad_perm:[1,0,3,2] row_mask:0xf bank_mask:0xf bound_ctrl:1
	v_add_f32_dpp v218, v218, v218 quad_perm:[1,0,3,2] row_mask:0xf bank_mask:0xf bound_ctrl:1
	v_pk_mul_f32 v[222:223], v[102:103], v[212:213] op_sel:[0,1]
	v_add_f32_dpp v216, v216, v216 quad_perm:[2,3,0,1] row_mask:0xf bank_mask:0xf bound_ctrl:1
	v_add_f32_dpp v218, v218, v218 quad_perm:[2,3,0,1] row_mask:0xf bank_mask:0xf bound_ctrl:1
	v_pk_fma_f32 v[220:221], v[0:1], v[104:105], v[220:221]
	v_add_f32_dpp v216, v216, v216 row_half_mirror row_mask:0xf bank_mask:0xf bound_ctrl:1
	v_add_f32_dpp v218, v218, v218 row_half_mirror row_mask:0xf bank_mask:0xf bound_ctrl:1
	v_pk_fma_f32 v[222:223], v[2:3], v[106:107], v[222:223]
	v_add_f32_dpp v216, v216, v216 row_mirror row_mask:0xf bank_mask:0xf bound_ctrl:1
	v_add_f32_dpp v226, v218, v218 row_mirror row_mask:0xf bank_mask:0xf bound_ctrl:1
	v_pk_fma_f32 v[0:1], v[112:113], v[216:217], v[220:221] op_sel_hi:[1,0,1] neg_lo:[1,0,0] neg_hi:[1,0,0]
	v_pk_fma_f32 v[2:3], v[114:115], v[216:217], v[222:223] op_sel_hi:[1,0,1] neg_lo:[1,0,0] neg_hi:[1,0,0]
	global_store_dword v5, v226, s[44:45] offset:-4096
	s_waitcnt lgkmcnt(5)
	ds_read2st64_b32 v[212:213], v4 offset0:8 offset1:9
	ds_read_b128 v[88:91], v8 offset:34816
	ds_read_b128 v[80:83], v8 offset:10240
	ds_read_b128 v[84:87], v8 offset:26624
	ds_read_b128 v[92:95], v8 offset:43008
	ds_read_b128 v[76:79], v8 offset:2048
	v_pk_mul_f32 v[216:217], v[0:1], v[184:185]
	v_pk_mul_f32 v[218:219], v[0:1], v[96:97]
	v_pk_fma_f32 v[216:217], v[2:3], v[186:187], v[216:217]
	v_pk_fma_f32 v[218:219], v[2:3], v[98:99], v[218:219]
	v_add_f32_e32 v216, v216, v217
	v_add_f32_e32 v218, v218, v219
	v_pk_mul_f32 v[220:221], v[176:177], v[214:215] op_sel_hi:[1,0]
	v_add_f32_dpp v216, v216, v216 quad_perm:[1,0,3,2] row_mask:0xf bank_mask:0xf bound_ctrl:1
	v_add_f32_dpp v218, v218, v218 quad_perm:[1,0,3,2] row_mask:0xf bank_mask:0xf bound_ctrl:1
	v_pk_mul_f32 v[222:223], v[178:179], v[214:215] op_sel_hi:[1,0]
	v_add_f32_dpp v216, v216, v216 quad_perm:[2,3,0,1] row_mask:0xf bank_mask:0xf bound_ctrl:1
	v_add_f32_dpp v218, v218, v218 quad_perm:[2,3,0,1] row_mask:0xf bank_mask:0xf bound_ctrl:1
	v_pk_fma_f32 v[220:221], v[0:1], v[180:181], v[220:221]
	v_add_f32_dpp v216, v216, v216 row_half_mirror row_mask:0xf bank_mask:0xf bound_ctrl:1
	v_add_f32_dpp v218, v218, v218 row_half_mirror row_mask:0xf bank_mask:0xf bound_ctrl:1
	v_pk_fma_f32 v[222:223], v[2:3], v[182:183], v[222:223]
	v_add_f32_dpp v216, v216, v216 row_mirror row_mask:0xf bank_mask:0xf bound_ctrl:1
	v_add_f32_dpp v227, v218, v218 row_mirror row_mask:0xf bank_mask:0xf bound_ctrl:1
	v_pk_fma_f32 v[0:1], v[188:189], v[216:217], v[220:221] op_sel_hi:[1,0,1] neg_lo:[1,0,0] neg_hi:[1,0,0]
	v_pk_fma_f32 v[2:3], v[190:191], v[216:217], v[222:223] op_sel_hi:[1,0,1] neg_lo:[1,0,0] neg_hi:[1,0,0]
	global_store_dword v5, v227, s[44:45] offset:0
	s_add_u32 s44, s44, 0x2000
	s_addc_u32 s45, s45, 0
	s_waitcnt lgkmcnt(6)
	ds_read_b128 v[108:111], v8 offset:35072
	ds_read_b128 v[100:103], v8 offset:10496
	ds_read_b128 v[104:107], v8 offset:26880
	ds_read_b128 v[112:115], v8 offset:43264
	ds_read_b128 v[96:99], v8 offset:2304
	v_pk_mul_f32 v[216:217], v[0:1], v[204:205]
	v_pk_mul_f32 v[218:219], v[0:1], v[172:173]
	v_pk_fma_f32 v[216:217], v[2:3], v[206:207], v[216:217]
	v_pk_fma_f32 v[218:219], v[2:3], v[174:175], v[218:219]
	v_add_f32_e32 v216, v216, v217
	v_add_f32_e32 v218, v218, v219
	v_pk_mul_f32 v[220:221], v[196:197], v[214:215] op_sel:[0,1]
	v_add_f32_dpp v216, v216, v216 quad_perm:[1,0,3,2] row_mask:0xf bank_mask:0xf bound_ctrl:1
	v_add_f32_dpp v218, v218, v218 quad_perm:[1,0,3,2] row_mask:0xf bank_mask:0xf bound_ctrl:1
	v_pk_mul_f32 v[222:223], v[198:199], v[214:215] op_sel:[0,1]
	v_add_f32_dpp v216, v216, v216 quad_perm:[2,3,0,1] row_mask:0xf bank_mask:0xf bound_ctrl:1
	v_add_f32_dpp v218, v218, v218 quad_perm:[2,3,0,1] row_mask:0xf bank_mask:0xf bound_ctrl:1
	v_pk_fma_f32 v[220:221], v[0:1], v[200:201], v[220:221]
	v_add_f32_dpp v216, v216, v216 row_half_mirror row_mask:0xf bank_mask:0xf bound_ctrl:1
	v_add_f32_dpp v218, v218, v218 row_half_mirror row_mask:0xf bank_mask:0xf bound_ctrl:1
	v_pk_fma_f32 v[222:223], v[2:3], v[202:203], v[222:223]
	v_add_f32_dpp v216, v216, v216 row_mirror row_mask:0xf bank_mask:0xf bound_ctrl:1
	v_add_f32_dpp v226, v218, v218 row_mirror row_mask:0xf bank_mask:0xf bound_ctrl:1
	v_pk_fma_f32 v[0:1], v[208:209], v[216:217], v[220:221] op_sel_hi:[1,0,1] neg_lo:[1,0,0] neg_hi:[1,0,0]
	v_pk_fma_f32 v[2:3], v[210:211], v[216:217], v[222:223] op_sel_hi:[1,0,1] neg_lo:[1,0,0] neg_hi:[1,0,0]
	global_store_dword v5, v226, s[44:45] offset:-4096
	s_waitcnt lgkmcnt(5)
	ds_read2st64_b32 v[214:215], v4 offset0:10 offset1:11
	ds_read_b128 v[184:187], v8 offset:35328
	ds_read_b128 v[176:179], v8 offset:10752
	ds_read_b128 v[180:183], v8 offset:27136
	ds_read_b128 v[188:191], v8 offset:43520
	ds_read_b128 v[172:175], v8 offset:2560
	v_pk_mul_f32 v[216:217], v[0:1], v[88:89]
	v_pk_mul_f32 v[218:219], v[0:1], v[192:193]
	v_pk_fma_f32 v[216:217], v[2:3], v[90:91], v[216:217]
	v_pk_fma_f32 v[218:219], v[2:3], v[194:195], v[218:219]
	v_add_f32_e32 v216, v216, v217
	v_add_f32_e32 v218, v218, v219
	v_pk_mul_f32 v[220:221], v[80:81], v[212:213] op_sel_hi:[1,0]
	v_add_f32_dpp v216, v216, v216 quad_perm:[1,0,3,2] row_mask:0xf bank_mask:0xf bound_ctrl:1
	v_add_f32_dpp v218, v218, v218 quad_perm:[1,0,3,2] row_mask:0xf bank_mask:0xf bound_ctrl:1
	v_pk_mul_f32 v[222:223], v[82:83], v[212:213] op_sel_hi:[1,0]
	v_add_f32_dpp v216, v216, v216 quad_perm:[2,3,0,1] row_mask:0xf bank_mask:0xf bound_ctrl:1
	v_add_f32_dpp v218, v218, v218 quad_perm:[2,3,0,1] row_mask:0xf bank_mask:0xf bound_ctrl:1
	v_pk_fma_f32 v[220:221], v[0:1], v[84:85], v[220:221]
	v_add_f32_dpp v216, v216, v216 row_half_mirror row_mask:0xf bank_mask:0xf bound_ctrl:1
	v_add_f32_dpp v218, v218, v218 row_half_mirror row_mask:0xf bank_mask:0xf bound_ctrl:1
	v_pk_fma_f32 v[222:223], v[2:3], v[86:87], v[222:223]
	v_add_f32_dpp v216, v216, v216 row_mirror row_mask:0xf bank_mask:0xf bound_ctrl:1
	v_add_f32_dpp v227, v218, v218 row_mirror row_mask:0xf bank_mask:0xf bound_ctrl:1
	v_pk_fma_f32 v[0:1], v[92:93], v[216:217], v[220:221] op_sel_hi:[1,0,1] neg_lo:[1,0,0] neg_hi:[1,0,0]
	v_pk_fma_f32 v[2:3], v[94:95], v[216:217], v[222:223] op_sel_hi:[1,0,1] neg_lo:[1,0,0] neg_hi:[1,0,0]
	global_store_dword v5, v227, s[44:45] offset:0
	s_add_u32 s44, s44, 0x2000
	s_addc_u32 s45, s45, 0
	s_waitcnt lgkmcnt(6)
	ds_read_b128 v[204:207], v8 offset:35584
	ds_read_b128 v[196:199], v8 offset:11008
	ds_read_b128 v[200:203], v8 offset:27392
	ds_read_b128 v[208:211], v8 offset:43776
	ds_read_b128 v[192:195], v8 offset:2816
	v_pk_mul_f32 v[216:217], v[0:1], v[108:109]
	v_pk_mul_f32 v[218:219], v[0:1], v[76:77]
	v_pk_fma_f32 v[216:217], v[2:3], v[110:111], v[216:217]
	v_pk_fma_f32 v[218:219], v[2:3], v[78:79], v[218:219]
	v_add_f32_e32 v216, v216, v217
	v_add_f32_e32 v218, v218, v219
	v_pk_mul_f32 v[220:221], v[100:101], v[212:213] op_sel:[0,1]
	v_add_f32_dpp v216, v216, v216 quad_perm:[1,0,3,2] row_mask:0xf bank_mask:0xf bound_ctrl:1
	v_add_f32_dpp v218, v218, v218 quad_perm:[1,0,3,2] row_mask:0xf bank_mask:0xf bound_ctrl:1
	v_pk_mul_f32 v[222:223], v[102:103], v[212:213] op_sel:[0,1]
	v_add_f32_dpp v216, v216, v216 quad_perm:[2,3,0,1] row_mask:0xf bank_mask:0xf bound_ctrl:1
	v_add_f32_dpp v218, v218, v218 quad_perm:[2,3,0,1] row_mask:0xf bank_mask:0xf bound_ctrl:1
	v_pk_fma_f32 v[220:221], v[0:1], v[104:105], v[220:221]
	v_add_f32_dpp v216, v216, v216 row_half_mirror row_mask:0xf bank_mask:0xf bound_ctrl:1
	v_add_f32_dpp v218, v218, v218 row_half_mirror row_mask:0xf bank_mask:0xf bound_ctrl:1
	v_pk_fma_f32 v[222:223], v[2:3], v[106:107], v[222:223]
	v_add_f32_dpp v216, v216, v216 row_mirror row_mask:0xf bank_mask:0xf bound_ctrl:1
	v_add_f32_dpp v226, v218, v218 row_mirror row_mask:0xf bank_mask:0xf bound_ctrl:1
	v_pk_fma_f32 v[0:1], v[112:113], v[216:217], v[220:221] op_sel_hi:[1,0,1] neg_lo:[1,0,0] neg_hi:[1,0,0]
	v_pk_fma_f32 v[2:3], v[114:115], v[216:217], v[222:223] op_sel_hi:[1,0,1] neg_lo:[1,0,0] neg_hi:[1,0,0]
	global_store_dword v5, v226, s[44:45] offset:-4096
	s_waitcnt lgkmcnt(5)
	ds_read2st64_b32 v[212:213], v4 offset0:12 offset1:13
	ds_read_b128 v[88:91], v8 offset:35840
	ds_read_b128 v[80:83], v8 offset:11264
	ds_read_b128 v[84:87], v8 offset:27648
	ds_read_b128 v[92:95], v8 offset:44032
	ds_read_b128 v[76:79], v8 offset:3072
	v_pk_mul_f32 v[216:217], v[0:1], v[184:185]
	v_pk_mul_f32 v[218:219], v[0:1], v[96:97]
	v_pk_fma_f32 v[216:217], v[2:3], v[186:187], v[216:217]
	v_pk_fma_f32 v[218:219], v[2:3], v[98:99], v[218:219]
	v_add_f32_e32 v216, v216, v217
	v_add_f32_e32 v218, v218, v219
	v_pk_mul_f32 v[220:221], v[176:177], v[214:215] op_sel_hi:[1,0]
	v_add_f32_dpp v216, v216, v216 quad_perm:[1,0,3,2] row_mask:0xf bank_mask:0xf bound_ctrl:1
	v_add_f32_dpp v218, v218, v218 quad_perm:[1,0,3,2] row_mask:0xf bank_mask:0xf bound_ctrl:1
	v_pk_mul_f32 v[222:223], v[178:179], v[214:215] op_sel_hi:[1,0]
	v_add_f32_dpp v216, v216, v216 quad_perm:[2,3,0,1] row_mask:0xf bank_mask:0xf bound_ctrl:1
	v_add_f32_dpp v218, v218, v218 quad_perm:[2,3,0,1] row_mask:0xf bank_mask:0xf bound_ctrl:1
	v_pk_fma_f32 v[220:221], v[0:1], v[180:181], v[220:221]
	v_add_f32_dpp v216, v216, v216 row_half_mirror row_mask:0xf bank_mask:0xf bound_ctrl:1
	v_add_f32_dpp v218, v218, v218 row_half_mirror row_mask:0xf bank_mask:0xf bound_ctrl:1
	v_pk_fma_f32 v[222:223], v[2:3], v[182:183], v[222:223]
	v_add_f32_dpp v216, v216, v216 row_mirror row_mask:0xf bank_mask:0xf bound_ctrl:1
	v_add_f32_dpp v227, v218, v218 row_mirror row_mask:0xf bank_mask:0xf bound_ctrl:1
	v_pk_fma_f32 v[0:1], v[188:189], v[216:217], v[220:221] op_sel_hi:[1,0,1] neg_lo:[1,0,0] neg_hi:[1,0,0]
	v_pk_fma_f32 v[2:3], v[190:191], v[216:217], v[222:223] op_sel_hi:[1,0,1] neg_lo:[1,0,0] neg_hi:[1,0,0]
	global_store_dword v5, v227, s[44:45] offset:0
	s_add_u32 s44, s44, 0x2000
	s_addc_u32 s45, s45, 0
	s_waitcnt lgkmcnt(6)
	ds_read_b128 v[108:111], v8 offset:36096
	ds_read_b128 v[100:103], v8 offset:11520
	ds_read_b128 v[104:107], v8 offset:27904
	ds_read_b128 v[112:115], v8 offset:44288
	ds_read_b128 v[96:99], v8 offset:3328
	v_pk_mul_f32 v[216:217], v[0:1], v[204:205]
	v_pk_mul_f32 v[218:219], v[0:1], v[172:173]
	v_pk_fma_f32 v[216:217], v[2:3], v[206:207], v[216:217]
	v_pk_fma_f32 v[218:219], v[2:3], v[174:175], v[218:219]
	v_add_f32_e32 v216, v216, v217
	v_add_f32_e32 v218, v218, v219
	v_pk_mul_f32 v[220:221], v[196:197], v[214:215] op_sel:[0,1]
	v_add_f32_dpp v216, v216, v216 quad_perm:[1,0,3,2] row_mask:0xf bank_mask:0xf bound_ctrl:1
	v_add_f32_dpp v218, v218, v218 quad_perm:[1,0,3,2] row_mask:0xf bank_mask:0xf bound_ctrl:1
	v_pk_mul_f32 v[222:223], v[198:199], v[214:215] op_sel:[0,1]
	v_add_f32_dpp v216, v216, v216 quad_perm:[2,3,0,1] row_mask:0xf bank_mask:0xf bound_ctrl:1
	v_add_f32_dpp v218, v218, v218 quad_perm:[2,3,0,1] row_mask:0xf bank_mask:0xf bound_ctrl:1
	v_pk_fma_f32 v[220:221], v[0:1], v[200:201], v[220:221]
	v_add_f32_dpp v216, v216, v216 row_half_mirror row_mask:0xf bank_mask:0xf bound_ctrl:1
	v_add_f32_dpp v218, v218, v218 row_half_mirror row_mask:0xf bank_mask:0xf bound_ctrl:1
	v_pk_fma_f32 v[222:223], v[2:3], v[202:203], v[222:223]
	v_add_f32_dpp v216, v216, v216 row_mirror row_mask:0xf bank_mask:0xf bound_ctrl:1
	v_add_f32_dpp v226, v218, v218 row_mirror row_mask:0xf bank_mask:0xf bound_ctrl:1
	v_pk_fma_f32 v[0:1], v[208:209], v[216:217], v[220:221] op_sel_hi:[1,0,1] neg_lo:[1,0,0] neg_hi:[1,0,0]
	v_pk_fma_f32 v[2:3], v[210:211], v[216:217], v[222:223] op_sel_hi:[1,0,1] neg_lo:[1,0,0] neg_hi:[1,0,0]
	global_store_dword v5, v226, s[44:45] offset:-4096
	s_waitcnt lgkmcnt(5)
	ds_read2st64_b32 v[214:215], v4 offset0:14 offset1:15
	ds_read_b128 v[184:187], v8 offset:36352
	ds_read_b128 v[176:179], v8 offset:11776
	ds_read_b128 v[180:183], v8 offset:28160
	ds_read_b128 v[188:191], v8 offset:44544
	ds_read_b128 v[172:175], v8 offset:3584
	v_pk_mul_f32 v[216:217], v[0:1], v[88:89]
	v_pk_mul_f32 v[218:219], v[0:1], v[192:193]
	v_pk_fma_f32 v[216:217], v[2:3], v[90:91], v[216:217]
	v_pk_fma_f32 v[218:219], v[2:3], v[194:195], v[218:219]
	v_add_f32_e32 v216, v216, v217
	v_add_f32_e32 v218, v218, v219
	v_pk_mul_f32 v[220:221], v[80:81], v[212:213] op_sel_hi:[1,0]
	v_add_f32_dpp v216, v216, v216 quad_perm:[1,0,3,2] row_mask:0xf bank_mask:0xf bound_ctrl:1
	v_add_f32_dpp v218, v218, v218 quad_perm:[1,0,3,2] row_mask:0xf bank_mask:0xf bound_ctrl:1
	v_pk_mul_f32 v[222:223], v[82:83], v[212:213] op_sel_hi:[1,0]
	v_add_f32_dpp v216, v216, v216 quad_perm:[2,3,0,1] row_mask:0xf bank_mask:0xf bound_ctrl:1
	v_add_f32_dpp v218, v218, v218 quad_perm:[2,3,0,1] row_mask:0xf bank_mask:0xf bound_ctrl:1
	v_pk_fma_f32 v[220:221], v[0:1], v[84:85], v[220:221]
	v_add_f32_dpp v216, v216, v216 row_half_mirror row_mask:0xf bank_mask:0xf bound_ctrl:1
	v_add_f32_dpp v218, v218, v218 row_half_mirror row_mask:0xf bank_mask:0xf bound_ctrl:1
	v_pk_fma_f32 v[222:223], v[2:3], v[86:87], v[222:223]
	v_add_f32_dpp v216, v216, v216 row_mirror row_mask:0xf bank_mask:0xf bound_ctrl:1
	v_add_f32_dpp v227, v218, v218 row_mirror row_mask:0xf bank_mask:0xf bound_ctrl:1
	v_pk_fma_f32 v[0:1], v[92:93], v[216:217], v[220:221] op_sel_hi:[1,0,1] neg_lo:[1,0,0] neg_hi:[1,0,0]
	v_pk_fma_f32 v[2:3], v[94:95], v[216:217], v[222:223] op_sel_hi:[1,0,1] neg_lo:[1,0,0] neg_hi:[1,0,0]
	global_store_dword v5, v227, s[44:45] offset:0
	s_add_u32 s44, s44, 0x2000
	s_addc_u32 s45, s45, 0
	s_waitcnt lgkmcnt(6)
	ds_read_b128 v[204:207], v8 offset:36608
	ds_read_b128 v[196:199], v8 offset:12032
	ds_read_b128 v[200:203], v8 offset:28416
	ds_read_b128 v[208:211], v8 offset:44800
	ds_read_b128 v[192:195], v8 offset:3840
	v_pk_mul_f32 v[216:217], v[0:1], v[108:109]
	v_pk_mul_f32 v[218:219], v[0:1], v[76:77]
	v_pk_fma_f32 v[216:217], v[2:3], v[110:111], v[216:217]
	v_pk_fma_f32 v[218:219], v[2:3], v[78:79], v[218:219]
	v_add_f32_e32 v216, v216, v217
	v_add_f32_e32 v218, v218, v219
	v_pk_mul_f32 v[220:221], v[100:101], v[212:213] op_sel:[0,1]
	v_add_f32_dpp v216, v216, v216 quad_perm:[1,0,3,2] row_mask:0xf bank_mask:0xf bound_ctrl:1
	v_add_f32_dpp v218, v218, v218 quad_perm:[1,0,3,2] row_mask:0xf bank_mask:0xf bound_ctrl:1
	v_pk_mul_f32 v[222:223], v[102:103], v[212:213] op_sel:[0,1]
	v_add_f32_dpp v216, v216, v216 quad_perm:[2,3,0,1] row_mask:0xf bank_mask:0xf bound_ctrl:1
	v_add_f32_dpp v218, v218, v218 quad_perm:[2,3,0,1] row_mask:0xf bank_mask:0xf bound_ctrl:1
	v_pk_fma_f32 v[220:221], v[0:1], v[104:105], v[220:221]
	v_add_f32_dpp v216, v216, v216 row_half_mirror row_mask:0xf bank_mask:0xf bound_ctrl:1
	v_add_f32_dpp v218, v218, v218 row_half_mirror row_mask:0xf bank_mask:0xf bound_ctrl:1
	v_pk_fma_f32 v[222:223], v[2:3], v[106:107], v[222:223]
	v_add_f32_dpp v216, v216, v216 row_mirror row_mask:0xf bank_mask:0xf bound_ctrl:1
	v_add_f32_dpp v226, v218, v218 row_mirror row_mask:0xf bank_mask:0xf bound_ctrl:1
	v_pk_fma_f32 v[0:1], v[112:113], v[216:217], v[220:221] op_sel_hi:[1,0,1] neg_lo:[1,0,0] neg_hi:[1,0,0]
	v_pk_fma_f32 v[2:3], v[114:115], v[216:217], v[222:223] op_sel_hi:[1,0,1] neg_lo:[1,0,0] neg_hi:[1,0,0]
	global_store_dword v5, v226, s[44:45] offset:-4096
	s_waitcnt lgkmcnt(5)
	ds_read2st64_b32 v[212:213], v4 offset0:16 offset1:17
	ds_read_b128 v[88:91], v8 offset:36864
	ds_read_b128 v[80:83], v8 offset:12288
	ds_read_b128 v[84:87], v8 offset:28672
	ds_read_b128 v[92:95], v8 offset:45056
	ds_read_b128 v[76:79], v8 offset:4096
	v_pk_mul_f32 v[216:217], v[0:1], v[184:185]
	v_pk_mul_f32 v[218:219], v[0:1], v[96:97]
	v_pk_fma_f32 v[216:217], v[2:3], v[186:187], v[216:217]
	v_pk_fma_f32 v[218:219], v[2:3], v[98:99], v[218:219]
	v_add_f32_e32 v216, v216, v217
	v_add_f32_e32 v218, v218, v219
	v_pk_mul_f32 v[220:221], v[176:177], v[214:215] op_sel_hi:[1,0]
	v_add_f32_dpp v216, v216, v216 quad_perm:[1,0,3,2] row_mask:0xf bank_mask:0xf bound_ctrl:1
	v_add_f32_dpp v218, v218, v218 quad_perm:[1,0,3,2] row_mask:0xf bank_mask:0xf bound_ctrl:1
	v_pk_mul_f32 v[222:223], v[178:179], v[214:215] op_sel_hi:[1,0]
	v_add_f32_dpp v216, v216, v216 quad_perm:[2,3,0,1] row_mask:0xf bank_mask:0xf bound_ctrl:1
	v_add_f32_dpp v218, v218, v218 quad_perm:[2,3,0,1] row_mask:0xf bank_mask:0xf bound_ctrl:1
	v_pk_fma_f32 v[220:221], v[0:1], v[180:181], v[220:221]
	v_add_f32_dpp v216, v216, v216 row_half_mirror row_mask:0xf bank_mask:0xf bound_ctrl:1
	v_add_f32_dpp v218, v218, v218 row_half_mirror row_mask:0xf bank_mask:0xf bound_ctrl:1
	v_pk_fma_f32 v[222:223], v[2:3], v[182:183], v[222:223]
	v_add_f32_dpp v216, v216, v216 row_mirror row_mask:0xf bank_mask:0xf bound_ctrl:1
	v_add_f32_dpp v227, v218, v218 row_mirror row_mask:0xf bank_mask:0xf bound_ctrl:1
	v_pk_fma_f32 v[0:1], v[188:189], v[216:217], v[220:221] op_sel_hi:[1,0,1] neg_lo:[1,0,0] neg_hi:[1,0,0]
	v_pk_fma_f32 v[2:3], v[190:191], v[216:217], v[222:223] op_sel_hi:[1,0,1] neg_lo:[1,0,0] neg_hi:[1,0,0]
	global_store_dword v5, v227, s[44:45] offset:0
	s_add_u32 s44, s44, 0x2000
	s_addc_u32 s45, s45, 0
	s_waitcnt lgkmcnt(6)
	ds_read_b128 v[108:111], v8 offset:37120
	ds_read_b128 v[100:103], v8 offset:12544
	ds_read_b128 v[104:107], v8 offset:28928
	ds_read_b128 v[112:115], v8 offset:45312
	ds_read_b128 v[96:99], v8 offset:4352
	v_pk_mul_f32 v[216:217], v[0:1], v[204:205]
	v_pk_mul_f32 v[218:219], v[0:1], v[172:173]
	v_pk_fma_f32 v[216:217], v[2:3], v[206:207], v[216:217]
	v_pk_fma_f32 v[218:219], v[2:3], v[174:175], v[218:219]
	v_add_f32_e32 v216, v216, v217
	v_add_f32_e32 v218, v218, v219
	v_pk_mul_f32 v[220:221], v[196:197], v[214:215] op_sel:[0,1]
	v_add_f32_dpp v216, v216, v216 quad_perm:[1,0,3,2] row_mask:0xf bank_mask:0xf bound_ctrl:1
	v_add_f32_dpp v218, v218, v218 quad_perm:[1,0,3,2] row_mask:0xf bank_mask:0xf bound_ctrl:1
	v_pk_mul_f32 v[222:223], v[198:199], v[214:215] op_sel:[0,1]
	v_add_f32_dpp v216, v216, v216 quad_perm:[2,3,0,1] row_mask:0xf bank_mask:0xf bound_ctrl:1
	v_add_f32_dpp v218, v218, v218 quad_perm:[2,3,0,1] row_mask:0xf bank_mask:0xf bound_ctrl:1
	v_pk_fma_f32 v[220:221], v[0:1], v[200:201], v[220:221]
	v_add_f32_dpp v216, v216, v216 row_half_mirror row_mask:0xf bank_mask:0xf bound_ctrl:1
	v_add_f32_dpp v218, v218, v218 row_half_mirror row_mask:0xf bank_mask:0xf bound_ctrl:1
	v_pk_fma_f32 v[222:223], v[2:3], v[202:203], v[222:223]
	v_add_f32_dpp v216, v216, v216 row_mirror row_mask:0xf bank_mask:0xf bound_ctrl:1
	v_add_f32_dpp v226, v218, v218 row_mirror row_mask:0xf bank_mask:0xf bound_ctrl:1
	v_pk_fma_f32 v[0:1], v[208:209], v[216:217], v[220:221] op_sel_hi:[1,0,1] neg_lo:[1,0,0] neg_hi:[1,0,0]
	v_pk_fma_f32 v[2:3], v[210:211], v[216:217], v[222:223] op_sel_hi:[1,0,1] neg_lo:[1,0,0] neg_hi:[1,0,0]
	global_store_dword v5, v226, s[44:45] offset:-4096
	s_waitcnt lgkmcnt(5)
	ds_read2st64_b32 v[214:215], v4 offset0:18 offset1:19
	ds_read_b128 v[184:187], v8 offset:37376
	ds_read_b128 v[176:179], v8 offset:12800
	ds_read_b128 v[180:183], v8 offset:29184
	ds_read_b128 v[188:191], v8 offset:45568
	ds_read_b128 v[172:175], v8 offset:4608
	v_pk_mul_f32 v[216:217], v[0:1], v[88:89]
	v_pk_mul_f32 v[218:219], v[0:1], v[192:193]
	v_pk_fma_f32 v[216:217], v[2:3], v[90:91], v[216:217]
	v_pk_fma_f32 v[218:219], v[2:3], v[194:195], v[218:219]
	v_add_f32_e32 v216, v216, v217
	v_add_f32_e32 v218, v218, v219
	v_pk_mul_f32 v[220:221], v[80:81], v[212:213] op_sel_hi:[1,0]
	v_add_f32_dpp v216, v216, v216 quad_perm:[1,0,3,2] row_mask:0xf bank_mask:0xf bound_ctrl:1
	v_add_f32_dpp v218, v218, v218 quad_perm:[1,0,3,2] row_mask:0xf bank_mask:0xf bound_ctrl:1
	v_pk_mul_f32 v[222:223], v[82:83], v[212:213] op_sel_hi:[1,0]
	v_add_f32_dpp v216, v216, v216 quad_perm:[2,3,0,1] row_mask:0xf bank_mask:0xf bound_ctrl:1
	v_add_f32_dpp v218, v218, v218 quad_perm:[2,3,0,1] row_mask:0xf bank_mask:0xf bound_ctrl:1
	v_pk_fma_f32 v[220:221], v[0:1], v[84:85], v[220:221]
	v_add_f32_dpp v216, v216, v216 row_half_mirror row_mask:0xf bank_mask:0xf bound_ctrl:1
	v_add_f32_dpp v218, v218, v218 row_half_mirror row_mask:0xf bank_mask:0xf bound_ctrl:1
	v_pk_fma_f32 v[222:223], v[2:3], v[86:87], v[222:223]
	v_add_f32_dpp v216, v216, v216 row_mirror row_mask:0xf bank_mask:0xf bound_ctrl:1
	v_add_f32_dpp v227, v218, v218 row_mirror row_mask:0xf bank_mask:0xf bound_ctrl:1
	v_pk_fma_f32 v[0:1], v[92:93], v[216:217], v[220:221] op_sel_hi:[1,0,1] neg_lo:[1,0,0] neg_hi:[1,0,0]
	v_pk_fma_f32 v[2:3], v[94:95], v[216:217], v[222:223] op_sel_hi:[1,0,1] neg_lo:[1,0,0] neg_hi:[1,0,0]
	global_store_dword v5, v227, s[44:45] offset:0
	s_add_u32 s44, s44, 0x2000
	s_addc_u32 s45, s45, 0
	s_waitcnt lgkmcnt(6)
	ds_read_b128 v[204:207], v8 offset:37632
	ds_read_b128 v[196:199], v8 offset:13056
	ds_read_b128 v[200:203], v8 offset:29440
	ds_read_b128 v[208:211], v8 offset:45824
	ds_read_b128 v[192:195], v8 offset:4864
	v_pk_mul_f32 v[216:217], v[0:1], v[108:109]
	v_pk_mul_f32 v[218:219], v[0:1], v[76:77]
	v_pk_fma_f32 v[216:217], v[2:3], v[110:111], v[216:217]
	v_pk_fma_f32 v[218:219], v[2:3], v[78:79], v[218:219]
	v_add_f32_e32 v216, v216, v217
	v_add_f32_e32 v218, v218, v219
	v_pk_mul_f32 v[220:221], v[100:101], v[212:213] op_sel:[0,1]
	v_add_f32_dpp v216, v216, v216 quad_perm:[1,0,3,2] row_mask:0xf bank_mask:0xf bound_ctrl:1
	v_add_f32_dpp v218, v218, v218 quad_perm:[1,0,3,2] row_mask:0xf bank_mask:0xf bound_ctrl:1
	v_pk_mul_f32 v[222:223], v[102:103], v[212:213] op_sel:[0,1]
	v_add_f32_dpp v216, v216, v216 quad_perm:[2,3,0,1] row_mask:0xf bank_mask:0xf bound_ctrl:1
	v_add_f32_dpp v218, v218, v218 quad_perm:[2,3,0,1] row_mask:0xf bank_mask:0xf bound_ctrl:1
	v_pk_fma_f32 v[220:221], v[0:1], v[104:105], v[220:221]
	v_add_f32_dpp v216, v216, v216 row_half_mirror row_mask:0xf bank_mask:0xf bound_ctrl:1
	v_add_f32_dpp v218, v218, v218 row_half_mirror row_mask:0xf bank_mask:0xf bound_ctrl:1
	v_pk_fma_f32 v[222:223], v[2:3], v[106:107], v[222:223]
	v_add_f32_dpp v216, v216, v216 row_mirror row_mask:0xf bank_mask:0xf bound_ctrl:1
	v_add_f32_dpp v226, v218, v218 row_mirror row_mask:0xf bank_mask:0xf bound_ctrl:1
	v_pk_fma_f32 v[0:1], v[112:113], v[216:217], v[220:221] op_sel_hi:[1,0,1] neg_lo:[1,0,0] neg_hi:[1,0,0]
	v_pk_fma_f32 v[2:3], v[114:115], v[216:217], v[222:223] op_sel_hi:[1,0,1] neg_lo:[1,0,0] neg_hi:[1,0,0]
	global_store_dword v5, v226, s[44:45] offset:-4096
	s_waitcnt lgkmcnt(5)
	ds_read2st64_b32 v[212:213], v4 offset0:20 offset1:21
	ds_read_b128 v[88:91], v8 offset:37888
	ds_read_b128 v[80:83], v8 offset:13312
	ds_read_b128 v[84:87], v8 offset:29696
	ds_read_b128 v[92:95], v8 offset:46080
	ds_read_b128 v[76:79], v8 offset:5120
	v_pk_mul_f32 v[216:217], v[0:1], v[184:185]
	v_pk_mul_f32 v[218:219], v[0:1], v[96:97]
	v_pk_fma_f32 v[216:217], v[2:3], v[186:187], v[216:217]
	v_pk_fma_f32 v[218:219], v[2:3], v[98:99], v[218:219]
	v_add_f32_e32 v216, v216, v217
	v_add_f32_e32 v218, v218, v219
	v_pk_mul_f32 v[220:221], v[176:177], v[214:215] op_sel_hi:[1,0]
	v_add_f32_dpp v216, v216, v216 quad_perm:[1,0,3,2] row_mask:0xf bank_mask:0xf bound_ctrl:1
	v_add_f32_dpp v218, v218, v218 quad_perm:[1,0,3,2] row_mask:0xf bank_mask:0xf bound_ctrl:1
	v_pk_mul_f32 v[222:223], v[178:179], v[214:215] op_sel_hi:[1,0]
	v_add_f32_dpp v216, v216, v216 quad_perm:[2,3,0,1] row_mask:0xf bank_mask:0xf bound_ctrl:1
	v_add_f32_dpp v218, v218, v218 quad_perm:[2,3,0,1] row_mask:0xf bank_mask:0xf bound_ctrl:1
	v_pk_fma_f32 v[220:221], v[0:1], v[180:181], v[220:221]
	v_add_f32_dpp v216, v216, v216 row_half_mirror row_mask:0xf bank_mask:0xf bound_ctrl:1
	v_add_f32_dpp v218, v218, v218 row_half_mirror row_mask:0xf bank_mask:0xf bound_ctrl:1
	v_pk_fma_f32 v[222:223], v[2:3], v[182:183], v[222:223]
	v_add_f32_dpp v216, v216, v216 row_mirror row_mask:0xf bank_mask:0xf bound_ctrl:1
	v_add_f32_dpp v227, v218, v218 row_mirror row_mask:0xf bank_mask:0xf bound_ctrl:1
	v_pk_fma_f32 v[0:1], v[188:189], v[216:217], v[220:221] op_sel_hi:[1,0,1] neg_lo:[1,0,0] neg_hi:[1,0,0]
	v_pk_fma_f32 v[2:3], v[190:191], v[216:217], v[222:223] op_sel_hi:[1,0,1] neg_lo:[1,0,0] neg_hi:[1,0,0]
	global_store_dword v5, v227, s[44:45] offset:0
	s_add_u32 s44, s44, 0x2000
	s_addc_u32 s45, s45, 0
	s_waitcnt lgkmcnt(6)
	ds_read_b128 v[108:111], v8 offset:38144
	ds_read_b128 v[100:103], v8 offset:13568
	ds_read_b128 v[104:107], v8 offset:29952
	ds_read_b128 v[112:115], v8 offset:46336
	ds_read_b128 v[96:99], v8 offset:5376
	v_pk_mul_f32 v[216:217], v[0:1], v[204:205]
	v_pk_mul_f32 v[218:219], v[0:1], v[172:173]
	v_pk_fma_f32 v[216:217], v[2:3], v[206:207], v[216:217]
	v_pk_fma_f32 v[218:219], v[2:3], v[174:175], v[218:219]
	v_add_f32_e32 v216, v216, v217
	v_add_f32_e32 v218, v218, v219
	v_pk_mul_f32 v[220:221], v[196:197], v[214:215] op_sel:[0,1]
	v_add_f32_dpp v216, v216, v216 quad_perm:[1,0,3,2] row_mask:0xf bank_mask:0xf bound_ctrl:1
	v_add_f32_dpp v218, v218, v218 quad_perm:[1,0,3,2] row_mask:0xf bank_mask:0xf bound_ctrl:1
	v_pk_mul_f32 v[222:223], v[198:199], v[214:215] op_sel:[0,1]
	v_add_f32_dpp v216, v216, v216 quad_perm:[2,3,0,1] row_mask:0xf bank_mask:0xf bound_ctrl:1
	v_add_f32_dpp v218, v218, v218 quad_perm:[2,3,0,1] row_mask:0xf bank_mask:0xf bound_ctrl:1
	v_pk_fma_f32 v[220:221], v[0:1], v[200:201], v[220:221]
	v_add_f32_dpp v216, v216, v216 row_half_mirror row_mask:0xf bank_mask:0xf bound_ctrl:1
	v_add_f32_dpp v218, v218, v218 row_half_mirror row_mask:0xf bank_mask:0xf bound_ctrl:1
	v_pk_fma_f32 v[222:223], v[2:3], v[202:203], v[222:223]
	v_add_f32_dpp v216, v216, v216 row_mirror row_mask:0xf bank_mask:0xf bound_ctrl:1
	v_add_f32_dpp v226, v218, v218 row_mirror row_mask:0xf bank_mask:0xf bound_ctrl:1
	v_pk_fma_f32 v[0:1], v[208:209], v[216:217], v[220:221] op_sel_hi:[1,0,1] neg_lo:[1,0,0] neg_hi:[1,0,0]
	v_pk_fma_f32 v[2:3], v[210:211], v[216:217], v[222:223] op_sel_hi:[1,0,1] neg_lo:[1,0,0] neg_hi:[1,0,0]
	global_store_dword v5, v226, s[44:45] offset:-4096
	s_waitcnt lgkmcnt(5)
	ds_read2st64_b32 v[214:215], v4 offset0:22 offset1:23
	ds_read_b128 v[184:187], v8 offset:38400
	ds_read_b128 v[176:179], v8 offset:13824
	ds_read_b128 v[180:183], v8 offset:30208
	ds_read_b128 v[188:191], v8 offset:46592
	ds_read_b128 v[172:175], v8 offset:5632
	v_pk_mul_f32 v[216:217], v[0:1], v[88:89]
	v_pk_mul_f32 v[218:219], v[0:1], v[192:193]
	v_pk_fma_f32 v[216:217], v[2:3], v[90:91], v[216:217]
	v_pk_fma_f32 v[218:219], v[2:3], v[194:195], v[218:219]
	v_add_f32_e32 v216, v216, v217
	v_add_f32_e32 v218, v218, v219
	v_pk_mul_f32 v[220:221], v[80:81], v[212:213] op_sel_hi:[1,0]
	v_add_f32_dpp v216, v216, v216 quad_perm:[1,0,3,2] row_mask:0xf bank_mask:0xf bound_ctrl:1
	v_add_f32_dpp v218, v218, v218 quad_perm:[1,0,3,2] row_mask:0xf bank_mask:0xf bound_ctrl:1
	v_pk_mul_f32 v[222:223], v[82:83], v[212:213] op_sel_hi:[1,0]
	v_add_f32_dpp v216, v216, v216 quad_perm:[2,3,0,1] row_mask:0xf bank_mask:0xf bound_ctrl:1
	v_add_f32_dpp v218, v218, v218 quad_perm:[2,3,0,1] row_mask:0xf bank_mask:0xf bound_ctrl:1
	v_pk_fma_f32 v[220:221], v[0:1], v[84:85], v[220:221]
	v_add_f32_dpp v216, v216, v216 row_half_mirror row_mask:0xf bank_mask:0xf bound_ctrl:1
	v_add_f32_dpp v218, v218, v218 row_half_mirror row_mask:0xf bank_mask:0xf bound_ctrl:1
	v_pk_fma_f32 v[222:223], v[2:3], v[86:87], v[222:223]
	v_add_f32_dpp v216, v216, v216 row_mirror row_mask:0xf bank_mask:0xf bound_ctrl:1
	v_add_f32_dpp v227, v218, v218 row_mirror row_mask:0xf bank_mask:0xf bound_ctrl:1
	v_pk_fma_f32 v[0:1], v[92:93], v[216:217], v[220:221] op_sel_hi:[1,0,1] neg_lo:[1,0,0] neg_hi:[1,0,0]
	v_pk_fma_f32 v[2:3], v[94:95], v[216:217], v[222:223] op_sel_hi:[1,0,1] neg_lo:[1,0,0] neg_hi:[1,0,0]
	global_store_dword v5, v227, s[44:45] offset:0
	s_add_u32 s44, s44, 0x2000
	s_addc_u32 s45, s45, 0
	s_waitcnt lgkmcnt(6)
	ds_read_b128 v[204:207], v8 offset:38656
	ds_read_b128 v[196:199], v8 offset:14080
	ds_read_b128 v[200:203], v8 offset:30464
	ds_read_b128 v[208:211], v8 offset:46848
	ds_read_b128 v[192:195], v8 offset:5888
	v_pk_mul_f32 v[216:217], v[0:1], v[108:109]
	v_pk_mul_f32 v[218:219], v[0:1], v[76:77]
	v_pk_fma_f32 v[216:217], v[2:3], v[110:111], v[216:217]
	v_pk_fma_f32 v[218:219], v[2:3], v[78:79], v[218:219]
	v_add_f32_e32 v216, v216, v217
	v_add_f32_e32 v218, v218, v219
	v_pk_mul_f32 v[220:221], v[100:101], v[212:213] op_sel:[0,1]
	v_add_f32_dpp v216, v216, v216 quad_perm:[1,0,3,2] row_mask:0xf bank_mask:0xf bound_ctrl:1
	v_add_f32_dpp v218, v218, v218 quad_perm:[1,0,3,2] row_mask:0xf bank_mask:0xf bound_ctrl:1
	v_pk_mul_f32 v[222:223], v[102:103], v[212:213] op_sel:[0,1]
	v_add_f32_dpp v216, v216, v216 quad_perm:[2,3,0,1] row_mask:0xf bank_mask:0xf bound_ctrl:1
	v_add_f32_dpp v218, v218, v218 quad_perm:[2,3,0,1] row_mask:0xf bank_mask:0xf bound_ctrl:1
	v_pk_fma_f32 v[220:221], v[0:1], v[104:105], v[220:221]
	v_add_f32_dpp v216, v216, v216 row_half_mirror row_mask:0xf bank_mask:0xf bound_ctrl:1
	v_add_f32_dpp v218, v218, v218 row_half_mirror row_mask:0xf bank_mask:0xf bound_ctrl:1
	v_pk_fma_f32 v[222:223], v[2:3], v[106:107], v[222:223]
	v_add_f32_dpp v216, v216, v216 row_mirror row_mask:0xf bank_mask:0xf bound_ctrl:1
	v_add_f32_dpp v226, v218, v218 row_mirror row_mask:0xf bank_mask:0xf bound_ctrl:1
	v_pk_fma_f32 v[0:1], v[112:113], v[216:217], v[220:221] op_sel_hi:[1,0,1] neg_lo:[1,0,0] neg_hi:[1,0,0]
	v_pk_fma_f32 v[2:3], v[114:115], v[216:217], v[222:223] op_sel_hi:[1,0,1] neg_lo:[1,0,0] neg_hi:[1,0,0]
	global_store_dword v5, v226, s[44:45] offset:-4096
	s_waitcnt lgkmcnt(5)
	ds_read2st64_b32 v[212:213], v4 offset0:24 offset1:25
	ds_read_b128 v[88:91], v8 offset:38912
	ds_read_b128 v[80:83], v8 offset:14336
	ds_read_b128 v[84:87], v8 offset:30720
	ds_read_b128 v[92:95], v8 offset:47104
	ds_read_b128 v[76:79], v8 offset:6144
	v_pk_mul_f32 v[216:217], v[0:1], v[184:185]
	v_pk_mul_f32 v[218:219], v[0:1], v[96:97]
	v_pk_fma_f32 v[216:217], v[2:3], v[186:187], v[216:217]
	v_pk_fma_f32 v[218:219], v[2:3], v[98:99], v[218:219]
	v_add_f32_e32 v216, v216, v217
	v_add_f32_e32 v218, v218, v219
	v_pk_mul_f32 v[220:221], v[176:177], v[214:215] op_sel_hi:[1,0]
	v_add_f32_dpp v216, v216, v216 quad_perm:[1,0,3,2] row_mask:0xf bank_mask:0xf bound_ctrl:1
	v_add_f32_dpp v218, v218, v218 quad_perm:[1,0,3,2] row_mask:0xf bank_mask:0xf bound_ctrl:1
	v_pk_mul_f32 v[222:223], v[178:179], v[214:215] op_sel_hi:[1,0]
	v_add_f32_dpp v216, v216, v216 quad_perm:[2,3,0,1] row_mask:0xf bank_mask:0xf bound_ctrl:1
	v_add_f32_dpp v218, v218, v218 quad_perm:[2,3,0,1] row_mask:0xf bank_mask:0xf bound_ctrl:1
	v_pk_fma_f32 v[220:221], v[0:1], v[180:181], v[220:221]
	v_add_f32_dpp v216, v216, v216 row_half_mirror row_mask:0xf bank_mask:0xf bound_ctrl:1
	v_add_f32_dpp v218, v218, v218 row_half_mirror row_mask:0xf bank_mask:0xf bound_ctrl:1
	v_pk_fma_f32 v[222:223], v[2:3], v[182:183], v[222:223]
	v_add_f32_dpp v216, v216, v216 row_mirror row_mask:0xf bank_mask:0xf bound_ctrl:1
	v_add_f32_dpp v227, v218, v218 row_mirror row_mask:0xf bank_mask:0xf bound_ctrl:1
	v_pk_fma_f32 v[0:1], v[188:189], v[216:217], v[220:221] op_sel_hi:[1,0,1] neg_lo:[1,0,0] neg_hi:[1,0,0]
	v_pk_fma_f32 v[2:3], v[190:191], v[216:217], v[222:223] op_sel_hi:[1,0,1] neg_lo:[1,0,0] neg_hi:[1,0,0]
	global_store_dword v5, v227, s[44:45] offset:0
	s_add_u32 s44, s44, 0x2000
	s_addc_u32 s45, s45, 0
	s_waitcnt lgkmcnt(6)
	ds_read_b128 v[108:111], v8 offset:39168
	ds_read_b128 v[100:103], v8 offset:14592
	ds_read_b128 v[104:107], v8 offset:30976
	ds_read_b128 v[112:115], v8 offset:47360
	ds_read_b128 v[96:99], v8 offset:6400
	v_pk_mul_f32 v[216:217], v[0:1], v[204:205]
	v_pk_mul_f32 v[218:219], v[0:1], v[172:173]
	v_pk_fma_f32 v[216:217], v[2:3], v[206:207], v[216:217]
	v_pk_fma_f32 v[218:219], v[2:3], v[174:175], v[218:219]
	v_add_f32_e32 v216, v216, v217
	v_add_f32_e32 v218, v218, v219
	v_pk_mul_f32 v[220:221], v[196:197], v[214:215] op_sel:[0,1]
	v_add_f32_dpp v216, v216, v216 quad_perm:[1,0,3,2] row_mask:0xf bank_mask:0xf bound_ctrl:1
	v_add_f32_dpp v218, v218, v218 quad_perm:[1,0,3,2] row_mask:0xf bank_mask:0xf bound_ctrl:1
	v_pk_mul_f32 v[222:223], v[198:199], v[214:215] op_sel:[0,1]
	v_add_f32_dpp v216, v216, v216 quad_perm:[2,3,0,1] row_mask:0xf bank_mask:0xf bound_ctrl:1
	v_add_f32_dpp v218, v218, v218 quad_perm:[2,3,0,1] row_mask:0xf bank_mask:0xf bound_ctrl:1
	v_pk_fma_f32 v[220:221], v[0:1], v[200:201], v[220:221]
	v_add_f32_dpp v216, v216, v216 row_half_mirror row_mask:0xf bank_mask:0xf bound_ctrl:1
	v_add_f32_dpp v218, v218, v218 row_half_mirror row_mask:0xf bank_mask:0xf bound_ctrl:1
	v_pk_fma_f32 v[222:223], v[2:3], v[202:203], v[222:223]
	v_add_f32_dpp v216, v216, v216 row_mirror row_mask:0xf bank_mask:0xf bound_ctrl:1
	v_add_f32_dpp v226, v218, v218 row_mirror row_mask:0xf bank_mask:0xf bound_ctrl:1
	v_pk_fma_f32 v[0:1], v[208:209], v[216:217], v[220:221] op_sel_hi:[1,0,1] neg_lo:[1,0,0] neg_hi:[1,0,0]
	v_pk_fma_f32 v[2:3], v[210:211], v[216:217], v[222:223] op_sel_hi:[1,0,1] neg_lo:[1,0,0] neg_hi:[1,0,0]
	global_store_dword v5, v226, s[44:45] offset:-4096
	s_waitcnt lgkmcnt(5)
	ds_read2st64_b32 v[214:215], v4 offset0:26 offset1:27
	ds_read_b128 v[184:187], v8 offset:39424
	ds_read_b128 v[176:179], v8 offset:14848
	ds_read_b128 v[180:183], v8 offset:31232
	ds_read_b128 v[188:191], v8 offset:47616
	ds_read_b128 v[172:175], v8 offset:6656
	v_pk_mul_f32 v[216:217], v[0:1], v[88:89]
	v_pk_mul_f32 v[218:219], v[0:1], v[192:193]
	v_pk_fma_f32 v[216:217], v[2:3], v[90:91], v[216:217]
	v_pk_fma_f32 v[218:219], v[2:3], v[194:195], v[218:219]
	v_add_f32_e32 v216, v216, v217
	v_add_f32_e32 v218, v218, v219
	v_pk_mul_f32 v[220:221], v[80:81], v[212:213] op_sel_hi:[1,0]
	v_add_f32_dpp v216, v216, v216 quad_perm:[1,0,3,2] row_mask:0xf bank_mask:0xf bound_ctrl:1
	v_add_f32_dpp v218, v218, v218 quad_perm:[1,0,3,2] row_mask:0xf bank_mask:0xf bound_ctrl:1
	v_pk_mul_f32 v[222:223], v[82:83], v[212:213] op_sel_hi:[1,0]
	v_add_f32_dpp v216, v216, v216 quad_perm:[2,3,0,1] row_mask:0xf bank_mask:0xf bound_ctrl:1
	v_add_f32_dpp v218, v218, v218 quad_perm:[2,3,0,1] row_mask:0xf bank_mask:0xf bound_ctrl:1
	v_pk_fma_f32 v[220:221], v[0:1], v[84:85], v[220:221]
	v_add_f32_dpp v216, v216, v216 row_half_mirror row_mask:0xf bank_mask:0xf bound_ctrl:1
	v_add_f32_dpp v218, v218, v218 row_half_mirror row_mask:0xf bank_mask:0xf bound_ctrl:1
	v_pk_fma_f32 v[222:223], v[2:3], v[86:87], v[222:223]
	v_add_f32_dpp v216, v216, v216 row_mirror row_mask:0xf bank_mask:0xf bound_ctrl:1
	v_add_f32_dpp v227, v218, v218 row_mirror row_mask:0xf bank_mask:0xf bound_ctrl:1
	v_pk_fma_f32 v[0:1], v[92:93], v[216:217], v[220:221] op_sel_hi:[1,0,1] neg_lo:[1,0,0] neg_hi:[1,0,0]
	v_pk_fma_f32 v[2:3], v[94:95], v[216:217], v[222:223] op_sel_hi:[1,0,1] neg_lo:[1,0,0] neg_hi:[1,0,0]
	global_store_dword v5, v227, s[44:45] offset:0
	s_add_u32 s44, s44, 0x2000
	s_addc_u32 s45, s45, 0
	s_waitcnt lgkmcnt(6)
	ds_read_b128 v[204:207], v8 offset:39680
	ds_read_b128 v[196:199], v8 offset:15104
	ds_read_b128 v[200:203], v8 offset:31488
	ds_read_b128 v[208:211], v8 offset:47872
	ds_read_b128 v[192:195], v8 offset:6912
	v_pk_mul_f32 v[216:217], v[0:1], v[108:109]
	v_pk_mul_f32 v[218:219], v[0:1], v[76:77]
	v_pk_fma_f32 v[216:217], v[2:3], v[110:111], v[216:217]
	v_pk_fma_f32 v[218:219], v[2:3], v[78:79], v[218:219]
	v_add_f32_e32 v216, v216, v217
	v_add_f32_e32 v218, v218, v219
	v_pk_mul_f32 v[220:221], v[100:101], v[212:213] op_sel:[0,1]
	v_add_f32_dpp v216, v216, v216 quad_perm:[1,0,3,2] row_mask:0xf bank_mask:0xf bound_ctrl:1
	v_add_f32_dpp v218, v218, v218 quad_perm:[1,0,3,2] row_mask:0xf bank_mask:0xf bound_ctrl:1
	v_pk_mul_f32 v[222:223], v[102:103], v[212:213] op_sel:[0,1]
	v_add_f32_dpp v216, v216, v216 quad_perm:[2,3,0,1] row_mask:0xf bank_mask:0xf bound_ctrl:1
	v_add_f32_dpp v218, v218, v218 quad_perm:[2,3,0,1] row_mask:0xf bank_mask:0xf bound_ctrl:1
	v_pk_fma_f32 v[220:221], v[0:1], v[104:105], v[220:221]
	v_add_f32_dpp v216, v216, v216 row_half_mirror row_mask:0xf bank_mask:0xf bound_ctrl:1
	v_add_f32_dpp v218, v218, v218 row_half_mirror row_mask:0xf bank_mask:0xf bound_ctrl:1
	v_pk_fma_f32 v[222:223], v[2:3], v[106:107], v[222:223]
	v_add_f32_dpp v216, v216, v216 row_mirror row_mask:0xf bank_mask:0xf bound_ctrl:1
	v_add_f32_dpp v226, v218, v218 row_mirror row_mask:0xf bank_mask:0xf bound_ctrl:1
	v_pk_fma_f32 v[0:1], v[112:113], v[216:217], v[220:221] op_sel_hi:[1,0,1] neg_lo:[1,0,0] neg_hi:[1,0,0]
	v_pk_fma_f32 v[2:3], v[114:115], v[216:217], v[222:223] op_sel_hi:[1,0,1] neg_lo:[1,0,0] neg_hi:[1,0,0]
	global_store_dword v5, v226, s[44:45] offset:-4096
	s_waitcnt lgkmcnt(5)
	ds_read2st64_b32 v[212:213], v4 offset0:28 offset1:29
	ds_read_b128 v[88:91], v8 offset:39936
	ds_read_b128 v[80:83], v8 offset:15360
	ds_read_b128 v[84:87], v8 offset:31744
	ds_read_b128 v[92:95], v8 offset:48128
	ds_read_b128 v[76:79], v8 offset:7168
	v_pk_mul_f32 v[216:217], v[0:1], v[184:185]
	v_pk_mul_f32 v[218:219], v[0:1], v[96:97]
	v_pk_fma_f32 v[216:217], v[2:3], v[186:187], v[216:217]
	v_pk_fma_f32 v[218:219], v[2:3], v[98:99], v[218:219]
	v_add_f32_e32 v216, v216, v217
	v_add_f32_e32 v218, v218, v219
	v_pk_mul_f32 v[220:221], v[176:177], v[214:215] op_sel_hi:[1,0]
	v_add_f32_dpp v216, v216, v216 quad_perm:[1,0,3,2] row_mask:0xf bank_mask:0xf bound_ctrl:1
	v_add_f32_dpp v218, v218, v218 quad_perm:[1,0,3,2] row_mask:0xf bank_mask:0xf bound_ctrl:1
	v_pk_mul_f32 v[222:223], v[178:179], v[214:215] op_sel_hi:[1,0]
	v_add_f32_dpp v216, v216, v216 quad_perm:[2,3,0,1] row_mask:0xf bank_mask:0xf bound_ctrl:1
	v_add_f32_dpp v218, v218, v218 quad_perm:[2,3,0,1] row_mask:0xf bank_mask:0xf bound_ctrl:1
	v_pk_fma_f32 v[220:221], v[0:1], v[180:181], v[220:221]
	v_add_f32_dpp v216, v216, v216 row_half_mirror row_mask:0xf bank_mask:0xf bound_ctrl:1
	v_add_f32_dpp v218, v218, v218 row_half_mirror row_mask:0xf bank_mask:0xf bound_ctrl:1
	v_pk_fma_f32 v[222:223], v[2:3], v[182:183], v[222:223]
	v_add_f32_dpp v216, v216, v216 row_mirror row_mask:0xf bank_mask:0xf bound_ctrl:1
	v_add_f32_dpp v227, v218, v218 row_mirror row_mask:0xf bank_mask:0xf bound_ctrl:1
	v_pk_fma_f32 v[0:1], v[188:189], v[216:217], v[220:221] op_sel_hi:[1,0,1] neg_lo:[1,0,0] neg_hi:[1,0,0]
	v_pk_fma_f32 v[2:3], v[190:191], v[216:217], v[222:223] op_sel_hi:[1,0,1] neg_lo:[1,0,0] neg_hi:[1,0,0]
	global_store_dword v5, v227, s[44:45] offset:0
	s_add_u32 s44, s44, 0x2000
	s_addc_u32 s45, s45, 0
	s_waitcnt lgkmcnt(6)
	ds_read_b128 v[108:111], v8 offset:40192
	ds_read_b128 v[100:103], v8 offset:15616
	ds_read_b128 v[104:107], v8 offset:32000
	ds_read_b128 v[112:115], v8 offset:48384
	ds_read_b128 v[96:99], v8 offset:7424
	v_pk_mul_f32 v[216:217], v[0:1], v[204:205]
	v_pk_mul_f32 v[218:219], v[0:1], v[172:173]
	v_pk_fma_f32 v[216:217], v[2:3], v[206:207], v[216:217]
	v_pk_fma_f32 v[218:219], v[2:3], v[174:175], v[218:219]
	v_add_f32_e32 v216, v216, v217
	v_add_f32_e32 v218, v218, v219
	v_pk_mul_f32 v[220:221], v[196:197], v[214:215] op_sel:[0,1]
	v_add_f32_dpp v216, v216, v216 quad_perm:[1,0,3,2] row_mask:0xf bank_mask:0xf bound_ctrl:1
	v_add_f32_dpp v218, v218, v218 quad_perm:[1,0,3,2] row_mask:0xf bank_mask:0xf bound_ctrl:1
	v_pk_mul_f32 v[222:223], v[198:199], v[214:215] op_sel:[0,1]
	v_add_f32_dpp v216, v216, v216 quad_perm:[2,3,0,1] row_mask:0xf bank_mask:0xf bound_ctrl:1
	v_add_f32_dpp v218, v218, v218 quad_perm:[2,3,0,1] row_mask:0xf bank_mask:0xf bound_ctrl:1
	v_pk_fma_f32 v[220:221], v[0:1], v[200:201], v[220:221]
	v_add_f32_dpp v216, v216, v216 row_half_mirror row_mask:0xf bank_mask:0xf bound_ctrl:1
	v_add_f32_dpp v218, v218, v218 row_half_mirror row_mask:0xf bank_mask:0xf bound_ctrl:1
	v_pk_fma_f32 v[222:223], v[2:3], v[202:203], v[222:223]
	v_add_f32_dpp v216, v216, v216 row_mirror row_mask:0xf bank_mask:0xf bound_ctrl:1
	v_add_f32_dpp v226, v218, v218 row_mirror row_mask:0xf bank_mask:0xf bound_ctrl:1
	v_pk_fma_f32 v[0:1], v[208:209], v[216:217], v[220:221] op_sel_hi:[1,0,1] neg_lo:[1,0,0] neg_hi:[1,0,0]
	v_pk_fma_f32 v[2:3], v[210:211], v[216:217], v[222:223] op_sel_hi:[1,0,1] neg_lo:[1,0,0] neg_hi:[1,0,0]
	global_store_dword v5, v226, s[44:45] offset:-4096
	s_waitcnt lgkmcnt(5)
	ds_read2st64_b32 v[214:215], v4 offset0:30 offset1:31
	ds_read_b128 v[184:187], v8 offset:40448
	ds_read_b128 v[176:179], v8 offset:15872
	ds_read_b128 v[180:183], v8 offset:32256
	ds_read_b128 v[188:191], v8 offset:48640
	ds_read_b128 v[172:175], v8 offset:7680
	v_pk_mul_f32 v[216:217], v[0:1], v[88:89]
	v_pk_mul_f32 v[218:219], v[0:1], v[192:193]
	v_pk_fma_f32 v[216:217], v[2:3], v[90:91], v[216:217]
	v_pk_fma_f32 v[218:219], v[2:3], v[194:195], v[218:219]
	v_add_f32_e32 v216, v216, v217
	v_add_f32_e32 v218, v218, v219
	v_pk_mul_f32 v[220:221], v[80:81], v[212:213] op_sel_hi:[1,0]
	v_add_f32_dpp v216, v216, v216 quad_perm:[1,0,3,2] row_mask:0xf bank_mask:0xf bound_ctrl:1
	v_add_f32_dpp v218, v218, v218 quad_perm:[1,0,3,2] row_mask:0xf bank_mask:0xf bound_ctrl:1
	v_pk_mul_f32 v[222:223], v[82:83], v[212:213] op_sel_hi:[1,0]
	v_add_f32_dpp v216, v216, v216 quad_perm:[2,3,0,1] row_mask:0xf bank_mask:0xf bound_ctrl:1
	v_add_f32_dpp v218, v218, v218 quad_perm:[2,3,0,1] row_mask:0xf bank_mask:0xf bound_ctrl:1
	v_pk_fma_f32 v[220:221], v[0:1], v[84:85], v[220:221]
	v_add_f32_dpp v216, v216, v216 row_half_mirror row_mask:0xf bank_mask:0xf bound_ctrl:1
	v_add_f32_dpp v218, v218, v218 row_half_mirror row_mask:0xf bank_mask:0xf bound_ctrl:1
	v_pk_fma_f32 v[222:223], v[2:3], v[86:87], v[222:223]
	v_add_f32_dpp v216, v216, v216 row_mirror row_mask:0xf bank_mask:0xf bound_ctrl:1
	v_add_f32_dpp v227, v218, v218 row_mirror row_mask:0xf bank_mask:0xf bound_ctrl:1
	v_pk_fma_f32 v[0:1], v[92:93], v[216:217], v[220:221] op_sel_hi:[1,0,1] neg_lo:[1,0,0] neg_hi:[1,0,0]
	v_pk_fma_f32 v[2:3], v[94:95], v[216:217], v[222:223] op_sel_hi:[1,0,1] neg_lo:[1,0,0] neg_hi:[1,0,0]
	global_store_dword v5, v227, s[44:45] offset:0
	s_add_u32 s44, s44, 0x2000
	s_addc_u32 s45, s45, 0
	s_waitcnt lgkmcnt(6)
	ds_read_b128 v[204:207], v8 offset:40704
	ds_read_b128 v[196:199], v8 offset:16128
	ds_read_b128 v[200:203], v8 offset:32512
	ds_read_b128 v[208:211], v8 offset:48896
	ds_read_b128 v[192:195], v8 offset:7936
	v_pk_mul_f32 v[216:217], v[0:1], v[108:109]
	v_pk_mul_f32 v[218:219], v[0:1], v[76:77]
	v_pk_fma_f32 v[216:217], v[2:3], v[110:111], v[216:217]
	v_pk_fma_f32 v[218:219], v[2:3], v[78:79], v[218:219]
	v_add_f32_e32 v216, v216, v217
	v_add_f32_e32 v218, v218, v219
	v_pk_mul_f32 v[220:221], v[100:101], v[212:213] op_sel:[0,1]
	v_add_f32_dpp v216, v216, v216 quad_perm:[1,0,3,2] row_mask:0xf bank_mask:0xf bound_ctrl:1
	v_add_f32_dpp v218, v218, v218 quad_perm:[1,0,3,2] row_mask:0xf bank_mask:0xf bound_ctrl:1
	v_pk_mul_f32 v[222:223], v[102:103], v[212:213] op_sel:[0,1]
	v_add_f32_dpp v216, v216, v216 quad_perm:[2,3,0,1] row_mask:0xf bank_mask:0xf bound_ctrl:1
	v_add_f32_dpp v218, v218, v218 quad_perm:[2,3,0,1] row_mask:0xf bank_mask:0xf bound_ctrl:1
	v_pk_fma_f32 v[220:221], v[0:1], v[104:105], v[220:221]
	v_add_f32_dpp v216, v216, v216 row_half_mirror row_mask:0xf bank_mask:0xf bound_ctrl:1
	v_add_f32_dpp v218, v218, v218 row_half_mirror row_mask:0xf bank_mask:0xf bound_ctrl:1
	v_pk_fma_f32 v[222:223], v[2:3], v[106:107], v[222:223]
	v_add_f32_dpp v216, v216, v216 row_mirror row_mask:0xf bank_mask:0xf bound_ctrl:1
	v_add_f32_dpp v226, v218, v218 row_mirror row_mask:0xf bank_mask:0xf bound_ctrl:1
	v_pk_fma_f32 v[0:1], v[112:113], v[216:217], v[220:221] op_sel_hi:[1,0,1] neg_lo:[1,0,0] neg_hi:[1,0,0]
	v_pk_fma_f32 v[2:3], v[114:115], v[216:217], v[222:223] op_sel_hi:[1,0,1] neg_lo:[1,0,0] neg_hi:[1,0,0]
	global_store_dword v5, v226, s[44:45] offset:-4096
	s_waitcnt lgkmcnt(5)
	v_pk_mul_f32 v[216:217], v[0:1], v[184:185]
	v_pk_mul_f32 v[218:219], v[0:1], v[96:97]
	v_pk_fma_f32 v[216:217], v[2:3], v[186:187], v[216:217]
	v_pk_fma_f32 v[218:219], v[2:3], v[98:99], v[218:219]
	v_add_f32_e32 v216, v216, v217
	v_add_f32_e32 v218, v218, v219
	v_pk_mul_f32 v[220:221], v[176:177], v[214:215] op_sel_hi:[1,0]
	v_add_f32_dpp v216, v216, v216 quad_perm:[1,0,3,2] row_mask:0xf bank_mask:0xf bound_ctrl:1
	v_add_f32_dpp v218, v218, v218 quad_perm:[1,0,3,2] row_mask:0xf bank_mask:0xf bound_ctrl:1
	v_pk_mul_f32 v[222:223], v[178:179], v[214:215] op_sel_hi:[1,0]
	v_add_f32_dpp v216, v216, v216 quad_perm:[2,3,0,1] row_mask:0xf bank_mask:0xf bound_ctrl:1
	v_add_f32_dpp v218, v218, v218 quad_perm:[2,3,0,1] row_mask:0xf bank_mask:0xf bound_ctrl:1
	v_pk_fma_f32 v[220:221], v[0:1], v[180:181], v[220:221]
	v_add_f32_dpp v216, v216, v216 row_half_mirror row_mask:0xf bank_mask:0xf bound_ctrl:1
	v_add_f32_dpp v218, v218, v218 row_half_mirror row_mask:0xf bank_mask:0xf bound_ctrl:1
	v_pk_fma_f32 v[222:223], v[2:3], v[182:183], v[222:223]
	v_add_f32_dpp v216, v216, v216 row_mirror row_mask:0xf bank_mask:0xf bound_ctrl:1
	v_add_f32_dpp v227, v218, v218 row_mirror row_mask:0xf bank_mask:0xf bound_ctrl:1
	v_pk_fma_f32 v[0:1], v[188:189], v[216:217], v[220:221] op_sel_hi:[1,0,1] neg_lo:[1,0,0] neg_hi:[1,0,0]
	v_pk_fma_f32 v[2:3], v[190:191], v[216:217], v[222:223] op_sel_hi:[1,0,1] neg_lo:[1,0,0] neg_hi:[1,0,0]
	global_store_dword v5, v227, s[44:45] offset:0
	s_add_u32 s44, s44, 0x2000
	s_addc_u32 s45, s45, 0
	s_waitcnt lgkmcnt(0)
	v_pk_mul_f32 v[216:217], v[0:1], v[204:205]
	v_pk_mul_f32 v[218:219], v[0:1], v[172:173]
	v_pk_fma_f32 v[216:217], v[2:3], v[206:207], v[216:217]
	v_pk_fma_f32 v[218:219], v[2:3], v[174:175], v[218:219]
	v_add_f32_e32 v216, v216, v217
	v_add_f32_e32 v218, v218, v219
	v_pk_mul_f32 v[220:221], v[196:197], v[214:215] op_sel:[0,1]
	v_add_f32_dpp v216, v216, v216 quad_perm:[1,0,3,2] row_mask:0xf bank_mask:0xf bound_ctrl:1
	v_add_f32_dpp v218, v218, v218 quad_perm:[1,0,3,2] row_mask:0xf bank_mask:0xf bound_ctrl:1
	v_pk_mul_f32 v[222:223], v[198:199], v[214:215] op_sel:[0,1]
	v_add_f32_dpp v216, v216, v216 quad_perm:[2,3,0,1] row_mask:0xf bank_mask:0xf bound_ctrl:1
	v_add_f32_dpp v218, v218, v218 quad_perm:[2,3,0,1] row_mask:0xf bank_mask:0xf bound_ctrl:1
	v_pk_fma_f32 v[220:221], v[0:1], v[200:201], v[220:221]
	v_add_f32_dpp v216, v216, v216 row_half_mirror row_mask:0xf bank_mask:0xf bound_ctrl:1
	v_add_f32_dpp v218, v218, v218 row_half_mirror row_mask:0xf bank_mask:0xf bound_ctrl:1
	v_pk_fma_f32 v[222:223], v[2:3], v[202:203], v[222:223]
	v_add_f32_dpp v216, v216, v216 row_mirror row_mask:0xf bank_mask:0xf bound_ctrl:1
	v_add_f32_dpp v226, v218, v218 row_mirror row_mask:0xf bank_mask:0xf bound_ctrl:1
	v_pk_fma_f32 v[0:1], v[208:209], v[216:217], v[220:221] op_sel_hi:[1,0,1] neg_lo:[1,0,0] neg_hi:[1,0,0]
	v_pk_fma_f32 v[2:3], v[210:211], v[216:217], v[222:223] op_sel_hi:[1,0,1] neg_lo:[1,0,0] neg_hi:[1,0,0]
	global_store_dword v5, v226, s[44:45] offset:-4096
	v_pk_mul_f32 v[218:219], v[0:1], v[192:193]
	v_pk_fma_f32 v[218:219], v[2:3], v[194:195], v[218:219]
	v_add_f32_e32 v218, v218, v219
	s_nop 1
	v_add_f32_dpp v218, v218, v218 quad_perm:[1,0,3,2] row_mask:0xf bank_mask:0xf bound_ctrl:1
	s_nop 1
	v_add_f32_dpp v218, v218, v218 quad_perm:[2,3,0,1] row_mask:0xf bank_mask:0xf bound_ctrl:1
	s_nop 1
	v_add_f32_dpp v218, v218, v218 row_half_mirror row_mask:0xf bank_mask:0xf bound_ctrl:1
	s_nop 1
	v_add_f32_dpp v227, v218, v218 row_mirror row_mask:0xf bank_mask:0xf bound_ctrl:1
	global_store_dword v5, v227, s[44:45] offset:0
